# SwiGLU epilogue: per-store blocks re-list-scheduled with renamed temporaries so the exp/rcp chains of four element pairs interleave (49 hazard nops gone)
# speedup vs baseline: 1.0026x; 1.0026x over previous
; DI unsigned pk2(float lo, float hi) { const f32x2 v = {lo, hi}; const hbf16x2 b = __builtin_convertvector(v, hbf16x2); return __builtin_bit_cast(unsigned, b); }
; DI float silu_f(float a) { return a * __builtin_amdgcn_rcpf(1.f + __builtin_amdgcn_exp2f(-a * LOG2E)); }
;     DI void operator()(const AccT& acc, const Unit& u, int wr, int wc, int fr, int fq) const {
;     ...
;         const int row0 = u.pm * 256 + wr * 64 + fr, col0 = u.pn * 128 + wc * 32 + 8 * fq;
; #pragma unroll
;         for (int ai = 0; ai < 2; ++ai)
; #pragma unroll
;             for (int m = 0; m < 4; ++m) {
;                 bf16_t* p = O + (size_t)(row0 + ai * 128 + m * 16) * FF + col0;
;                 float v[8];
; #pragma unroll
;                 for (int n = 0; n < 2; ++n)
; #pragma unroll
;                     for (int i = 0; i < 4; ++i) v[n * 4 + i] = silu_f(acc[ai][0][m][n][i]) * acc[ai][1][m][n][i];
;                 u32x4 w; w.x = pk2(v[0], v[1]); w.y = pk2(v[2], v[3]); w.z = pk2(v[4], v[5]); w.w = pk2(v[6], v[7]);
;                 *(u32x4*)p = w; __builtin_amdgcn_sched_barrier(0);
.LBB0_474:
	v_mov_b32_e32 v138, v141
	v_mov_b32_e32 v139, v140
	s_lshl_b32 s20, s50, 8
	s_add_i32 s20, s20, s64
	v_add_u32_e32 v144, s20, v139
	v_mul_f32_e32 v139, 0xbfb8aa3b, v124
	v_exp_f32_e32 v139, v139
	v_mul_f32_e32 v145, 0xbfb8aa3b, v125
	v_exp_f32_e32 v145, v145
	v_mul_f32_e32 v157, 0xbfb8aa3b, v127
	v_add_f32_e32 v139, 1.0, v139
	v_rcp_f32_e32 v158, v139
	v_add_f32_e32 v139, 1.0, v145
	v_rcp_f32_e32 v159, v139
	v_mul_f32_e32 v145, 0xbfb8aa3b, v126
	v_exp_f32_e32 v145, v145
	v_exp_f32_e32 v157, v157
	v_pk_mul_f32 v[124:125], v[124:125], v[158:159]
	s_lshl_b32 s20, s37, 7
	v_pk_mul_f32 v[116:117], v[116:117], v[124:125]
	v_add_f32_e32 v124, 1.0, v145
	v_add_f32_e32 v125, 1.0, v157
	v_mul_f32_e32 v145, 0xbfb8aa3b, v120
	v_rcp_f32_e32 v124, v124
	v_rcp_f32_e32 v125, v125
	v_exp_f32_e32 v145, v145
	v_mul_f32_e32 v157, 0xbfb8aa3b, v121
	v_exp_f32_e32 v157, v157
	v_pk_mul_f32 v[124:125], v[126:127], v[124:125]
	v_add_f32_e32 v126, 1.0, v145
	v_mul_f32_e32 v145, 0xbfb8aa3b, v122
	v_add_f32_e32 v127, 1.0, v157
	v_exp_f32_e32 v145, v145
	v_mul_f32_e32 v157, 0xbfb8aa3b, v123
	v_exp_f32_e32 v157, v157
	v_rcp_f32_e32 v126, v126
	v_add_f32_e32 v145, 1.0, v145
	v_rcp_f32_e32 v127, v127
	v_rcp_f32_e32 v158, v145
	v_add_f32_e32 v145, 1.0, v157
	v_rcp_f32_e32 v159, v145
	s_or_b32 s20, s20, s65
	v_lshl_add_u32 v138, v138, 3, s20
	v_pk_mul_f32 v[120:121], v[120:121], v[126:127]
	v_ashrrev_i32_e32 v139, 31, v138
	v_pk_mul_f32 v[120:121], v[112:113], v[120:121]
	v_pk_mul_f32 v[112:113], v[122:123], v[158:159]
	v_lshl_add_u64 v[138:139], v[138:139], 1, s[4:5]
	v_pk_mul_f32 v[118:119], v[118:119], v[124:125]
	v_pk_mul_f32 v[122:123], v[114:115], v[112:113]
	s_movk_i32 s1, 0x1600
	v_mad_i64_i32 v[124:125], s[30:31], v144, s1, v[138:139]
	v_cvt_pk_bf16_f32 v112, v116, v117
	v_cvt_pk_bf16_f32 v113, v118, v119
	v_cvt_pk_bf16_f32 v114, v120, v121
	v_cvt_pk_bf16_f32 v115, v122, v123
	global_store_dwordx4 v[124:125], v[112:115], off
	s_nop 1
	v_mul_f32_e32 v170, 0xbfb8aa3b, v108
	v_mul_f32_e32 v171, 0xbfb8aa3b, v109
	v_add_u32_e32 v114, 16, v144
	v_mul_f32_e32 v172, 0xbfb8aa3b, v110
	v_exp_f32_e32 v170, v170
	v_exp_f32_e32 v171, v171
	v_mul_f32_e32 v173, 0xbfb8aa3b, v111
	v_exp_f32_e32 v172, v172
	v_add_f32_e32 v170, 1.0, v170
	v_add_f32_e32 v171, 1.0, v171
	v_exp_f32_e32 v173, v173
	v_add_f32_e32 v172, 1.0, v172
	v_rcp_f32_e32 v170, v170
	v_rcp_f32_e32 v171, v171
	v_add_f32_e32 v173, 1.0, v173
	v_rcp_f32_e32 v172, v172
	v_mul_f32_e32 v174, 0xbfb8aa3b, v100
	v_pk_mul_f32 v[108:109], v[108:109], v[170:171]
	v_rcp_f32_e32 v173, v173
	v_mul_f32_e32 v175, 0xbfb8aa3b, v101
	v_exp_f32_e32 v174, v174
	v_pk_mul_f32 v[104:105], v[104:105], v[108:109]
	v_pk_mul_f32 v[172:173], v[110:111], v[172:173]
	v_exp_f32_e32 v175, v175
	v_add_f32_e32 v174, 1.0, v174
	v_mul_f32_e32 v176, 0xbfb8aa3b, v102
	v_pk_mul_f32 v[106:107], v[106:107], v[172:173]
	v_add_f32_e32 v175, 1.0, v175
	v_rcp_f32_e32 v174, v174
	v_mul_f32_e32 v177, 0xbfb8aa3b, v103
	v_exp_f32_e32 v176, v176
	v_rcp_f32_e32 v175, v175
	v_mad_i64_i32 v[108:109], s[30:31], v114, s1, v[138:139]
	v_exp_f32_e32 v177, v177
	v_add_f32_e32 v176, 1.0, v176
	v_pk_mul_f32 v[100:101], v[100:101], v[174:175]
	v_add_f32_e32 v177, 1.0, v177
	v_rcp_f32_e32 v176, v176
	v_pk_mul_f32 v[100:101], v[96:97], v[100:101]
	v_rcp_f32_e32 v177, v177
	v_cvt_pk_bf16_f32 v96, v104, v105
	v_cvt_pk_bf16_f32 v97, v106, v107
	v_pk_mul_f32 v[176:177], v[102:103], v[176:177]
	s_nop 0
	v_pk_mul_f32 v[102:103], v[98:99], v[176:177]
	v_cvt_pk_bf16_f32 v98, v100, v101
	v_cvt_pk_bf16_f32 v99, v102, v103
	global_store_dwordx4 v[108:109], v[96:99], off
	s_nop 1
	v_mul_f32_e32 v170, 0xbfb8aa3b, v92
	v_mul_f32_e32 v171, 0xbfb8aa3b, v93
	v_add_u32_e32 v98, 32, v144
	v_mul_f32_e32 v172, 0xbfb8aa3b, v94
	v_exp_f32_e32 v170, v170
	v_exp_f32_e32 v171, v171
	v_mul_f32_e32 v173, 0xbfb8aa3b, v95
	v_exp_f32_e32 v172, v172
	v_add_f32_e32 v170, 1.0, v170
	v_add_f32_e32 v171, 1.0, v171
	v_exp_f32_e32 v173, v173
	v_add_f32_e32 v172, 1.0, v172
	v_rcp_f32_e32 v170, v170
	v_rcp_f32_e32 v171, v171
	v_add_f32_e32 v173, 1.0, v173
	v_rcp_f32_e32 v172, v172
	v_mul_f32_e32 v174, 0xbfb8aa3b, v84
	v_pk_mul_f32 v[92:93], v[92:93], v[170:171]
	v_rcp_f32_e32 v173, v173
	v_mul_f32_e32 v175, 0xbfb8aa3b, v85
	v_exp_f32_e32 v174, v174
	v_pk_mul_f32 v[88:89], v[88:89], v[92:93]
	v_pk_mul_f32 v[172:173], v[94:95], v[172:173]
	v_exp_f32_e32 v175, v175
	v_add_f32_e32 v174, 1.0, v174
	v_mul_f32_e32 v176, 0xbfb8aa3b, v86
	v_pk_mul_f32 v[90:91], v[90:91], v[172:173]
	v_add_f32_e32 v175, 1.0, v175
	v_rcp_f32_e32 v174, v174
	v_mul_f32_e32 v177, 0xbfb8aa3b, v87
	v_exp_f32_e32 v176, v176
	v_rcp_f32_e32 v175, v175
	v_mad_i64_i32 v[92:93], s[30:31], v98, s1, v[138:139]
	v_exp_f32_e32 v177, v177
	v_add_f32_e32 v176, 1.0, v176
	v_pk_mul_f32 v[84:85], v[84:85], v[174:175]
	v_add_f32_e32 v177, 1.0, v177
	v_rcp_f32_e32 v176, v176
	v_pk_mul_f32 v[84:85], v[80:81], v[84:85]
	v_rcp_f32_e32 v177, v177
	v_cvt_pk_bf16_f32 v80, v88, v89
	v_cvt_pk_bf16_f32 v81, v90, v91
	v_pk_mul_f32 v[176:177], v[86:87], v[176:177]
	s_nop 0
	v_pk_mul_f32 v[86:87], v[82:83], v[176:177]
	v_cvt_pk_bf16_f32 v82, v84, v85
	v_cvt_pk_bf16_f32 v83, v86, v87
	global_store_dwordx4 v[92:93], v[80:83], off
	s_nop 1
	v_mul_f32_e32 v170, 0xbfb8aa3b, v76
	v_mul_f32_e32 v171, 0xbfb8aa3b, v77
	v_add_u32_e32 v82, 48, v144
	v_mul_f32_e32 v172, 0xbfb8aa3b, v78
	v_exp_f32_e32 v170, v170
	v_exp_f32_e32 v171, v171
	v_mul_f32_e32 v173, 0xbfb8aa3b, v79
	v_exp_f32_e32 v172, v172
	v_add_f32_e32 v170, 1.0, v170
	v_add_f32_e32 v171, 1.0, v171
	v_exp_f32_e32 v173, v173
	v_add_f32_e32 v172, 1.0, v172
	v_rcp_f32_e32 v170, v170
	v_rcp_f32_e32 v171, v171
; DI unsigned pk2(float lo, float hi) { const f32x2 v = {lo, hi}; const hbf16x2 b = __builtin_convertvector(v, hbf16x2); return __builtin_bit_cast(unsigned, b); }
; DI float silu_f(float a) { return a * __builtin_amdgcn_rcpf(1.f + __builtin_amdgcn_exp2f(-a * LOG2E)); }
;     DI void operator()(const AccT& acc, const Unit& u, int wr, int wc, int fr, int fq) const {
;     ...
;         const int row0 = u.pm * 256 + wr * 64 + fr, col0 = u.pn * 128 + wc * 32 + 8 * fq;
; #pragma unroll
;         for (int ai = 0; ai < 2; ++ai)
; #pragma unroll
;             for (int m = 0; m < 4; ++m) {
;                 bf16_t* p = O + (size_t)(row0 + ai * 128 + m * 16) * FF + col0;
;                 float v[8];
; #pragma unroll
;                 for (int n = 0; n < 2; ++n)
; #pragma unroll
;                     for (int i = 0; i < 4; ++i) v[n * 4 + i] = silu_f(acc[ai][0][m][n][i]) * acc[ai][1][m][n][i];
;                 u32x4 w; w.x = pk2(v[0], v[1]); w.y = pk2(v[2], v[3]); w.z = pk2(v[4], v[5]); w.w = pk2(v[6], v[7]);
;                 *(u32x4*)p = w; __builtin_amdgcn_sched_barrier(0);
	v_add_f32_e32 v173, 1.0, v173
	v_rcp_f32_e32 v172, v172
	v_mul_f32_e32 v174, 0xbfb8aa3b, v68
	v_pk_mul_f32 v[76:77], v[76:77], v[170:171]
	v_rcp_f32_e32 v173, v173
	v_mul_f32_e32 v175, 0xbfb8aa3b, v69
	v_exp_f32_e32 v174, v174
	v_pk_mul_f32 v[72:73], v[72:73], v[76:77]
	v_pk_mul_f32 v[172:173], v[78:79], v[172:173]
	v_exp_f32_e32 v175, v175
	v_add_f32_e32 v174, 1.0, v174
	v_mul_f32_e32 v176, 0xbfb8aa3b, v70
	v_pk_mul_f32 v[74:75], v[74:75], v[172:173]
	v_add_f32_e32 v175, 1.0, v175
	v_rcp_f32_e32 v174, v174
	v_mul_f32_e32 v177, 0xbfb8aa3b, v71
	v_exp_f32_e32 v176, v176
	v_rcp_f32_e32 v175, v175
	v_mad_i64_i32 v[76:77], s[30:31], v82, s1, v[138:139]
	v_exp_f32_e32 v177, v177
	v_add_f32_e32 v176, 1.0, v176
	v_pk_mul_f32 v[68:69], v[68:69], v[174:175]
	v_add_f32_e32 v177, 1.0, v177
	v_rcp_f32_e32 v176, v176
	v_pk_mul_f32 v[68:69], v[64:65], v[68:69]
	v_rcp_f32_e32 v177, v177
	v_cvt_pk_bf16_f32 v64, v72, v73
	v_cvt_pk_bf16_f32 v65, v74, v75
	v_pk_mul_f32 v[176:177], v[70:71], v[176:177]
	s_nop 0
	v_pk_mul_f32 v[70:71], v[66:67], v[176:177]
	v_cvt_pk_bf16_f32 v66, v68, v69
	v_cvt_pk_bf16_f32 v67, v70, v71
	global_store_dwordx4 v[76:77], v[64:67], off
	s_nop 1
	v_mul_f32_e32 v170, 0xbfb8aa3b, v60
	v_mul_f32_e32 v171, 0xbfb8aa3b, v61
	v_add_u32_e32 v66, 0x80, v144
	v_mul_f32_e32 v172, 0xbfb8aa3b, v62
	v_exp_f32_e32 v170, v170
	v_exp_f32_e32 v171, v171
	v_mul_f32_e32 v173, 0xbfb8aa3b, v63
	v_exp_f32_e32 v172, v172
	v_add_f32_e32 v170, 1.0, v170
	v_add_f32_e32 v171, 1.0, v171
	v_exp_f32_e32 v173, v173
	v_add_f32_e32 v172, 1.0, v172
	v_rcp_f32_e32 v170, v170
	v_rcp_f32_e32 v171, v171
	v_add_f32_e32 v173, 1.0, v173
	v_rcp_f32_e32 v172, v172
	v_mul_f32_e32 v174, 0xbfb8aa3b, v52
	v_pk_mul_f32 v[60:61], v[60:61], v[170:171]
	v_rcp_f32_e32 v173, v173
	v_mul_f32_e32 v175, 0xbfb8aa3b, v53
	v_exp_f32_e32 v174, v174
	v_pk_mul_f32 v[56:57], v[56:57], v[60:61]
	v_pk_mul_f32 v[172:173], v[62:63], v[172:173]
	v_exp_f32_e32 v175, v175
	v_add_f32_e32 v174, 1.0, v174
	v_mul_f32_e32 v176, 0xbfb8aa3b, v54
	v_pk_mul_f32 v[58:59], v[58:59], v[172:173]
	v_add_f32_e32 v175, 1.0, v175
	v_rcp_f32_e32 v174, v174
	v_mul_f32_e32 v177, 0xbfb8aa3b, v55
	v_exp_f32_e32 v176, v176
	v_rcp_f32_e32 v175, v175
	v_mad_i64_i32 v[60:61], s[30:31], v66, s1, v[138:139]
	v_exp_f32_e32 v177, v177
	v_add_f32_e32 v176, 1.0, v176
	v_pk_mul_f32 v[52:53], v[52:53], v[174:175]
	v_add_f32_e32 v177, 1.0, v177
	v_rcp_f32_e32 v176, v176
	v_pk_mul_f32 v[52:53], v[48:49], v[52:53]
	v_rcp_f32_e32 v177, v177
	v_cvt_pk_bf16_f32 v48, v56, v57
	v_cvt_pk_bf16_f32 v49, v58, v59
	v_pk_mul_f32 v[176:177], v[54:55], v[176:177]
	s_nop 0
	v_pk_mul_f32 v[54:55], v[50:51], v[176:177]
	v_cvt_pk_bf16_f32 v50, v52, v53
	v_cvt_pk_bf16_f32 v51, v54, v55
	global_store_dwordx4 v[60:61], v[48:51], off
	s_nop 1
	v_mul_f32_e32 v170, 0xbfb8aa3b, v44
	v_mul_f32_e32 v171, 0xbfb8aa3b, v45
	v_add_u32_e32 v50, 0x90, v144
	v_mul_f32_e32 v172, 0xbfb8aa3b, v46
	v_exp_f32_e32 v170, v170
	v_exp_f32_e32 v171, v171
	v_mul_f32_e32 v173, 0xbfb8aa3b, v47
	v_exp_f32_e32 v172, v172
	v_add_f32_e32 v170, 1.0, v170
	v_add_f32_e32 v171, 1.0, v171
	v_exp_f32_e32 v173, v173
	v_add_f32_e32 v172, 1.0, v172
	v_rcp_f32_e32 v170, v170
	v_rcp_f32_e32 v171, v171
	v_add_f32_e32 v173, 1.0, v173
	v_rcp_f32_e32 v172, v172
	v_mul_f32_e32 v174, 0xbfb8aa3b, v36
	v_pk_mul_f32 v[44:45], v[44:45], v[170:171]
	v_rcp_f32_e32 v173, v173
	v_mul_f32_e32 v175, 0xbfb8aa3b, v37
	v_exp_f32_e32 v174, v174
	v_pk_mul_f32 v[40:41], v[40:41], v[44:45]
	v_pk_mul_f32 v[172:173], v[46:47], v[172:173]
	v_exp_f32_e32 v175, v175
	v_add_f32_e32 v174, 1.0, v174
	v_mul_f32_e32 v176, 0xbfb8aa3b, v38
	v_pk_mul_f32 v[42:43], v[42:43], v[172:173]
	v_add_f32_e32 v175, 1.0, v175
	v_rcp_f32_e32 v174, v174
	v_mul_f32_e32 v177, 0xbfb8aa3b, v39
	v_exp_f32_e32 v176, v176
	v_rcp_f32_e32 v175, v175
	v_mad_i64_i32 v[44:45], s[30:31], v50, s1, v[138:139]
; DI unsigned pk2(float lo, float hi) { const f32x2 v = {lo, hi}; const hbf16x2 b = __builtin_convertvector(v, hbf16x2); return __builtin_bit_cast(unsigned, b); }
; DI float silu_f(float a) { return a * __builtin_amdgcn_rcpf(1.f + __builtin_amdgcn_exp2f(-a * LOG2E)); }
; #define PG8_BAR __builtin_amdgcn_s_barrier()
; template <class Epi>
; DI void gemm_phase(LAS unsigned char* lds, const Gemm g, const StaticOrder S, const Epi E) {
;     ...
;         if (wr == 0) PG8_BAR;
;         E(acc, cur, wr, wc, fr, fq);
;         if (!has_next) break;
; #pragma unroll
;         for (int a = 0; a < 2; ++a)
; #pragma unroll
;             for (int b = 0; b < 2; ++b)
; #pragma unroll
;                 for (int m = 0; m < 4; ++m)
; #pragma unroll
;                     for (int n = 0; n < 2; ++n) acc[a][b][m][n] = (f32x4){0.f, 0.f, 0.f, 0.f};
;         cur = nxt; cA = nA; cB = nB; ++ui;
;         if (wr == 1) PG8_BAR;
;     DI void operator()(const AccT& acc, const Unit& u, int wr, int wc, int fr, int fq) const {
;     ...
;         const int row0 = u.pm * 256 + wr * 64 + fr, col0 = u.pn * 128 + wc * 32 + 8 * fq;
; #pragma unroll
;         for (int ai = 0; ai < 2; ++ai)
; #pragma unroll
;             for (int m = 0; m < 4; ++m) {
;                 bf16_t* p = O + (size_t)(row0 + ai * 128 + m * 16) * FF + col0;
;                 float v[8];
; #pragma unroll
;                 for (int n = 0; n < 2; ++n)
; #pragma unroll
;                     for (int i = 0; i < 4; ++i) v[n * 4 + i] = silu_f(acc[ai][0][m][n][i]) * acc[ai][1][m][n][i];
;                 u32x4 w; w.x = pk2(v[0], v[1]); w.y = pk2(v[2], v[3]); w.z = pk2(v[4], v[5]); w.w = pk2(v[6], v[7]);
;                 *(u32x4*)p = w; __builtin_amdgcn_sched_barrier(0);
;             }
;     }
	v_exp_f32_e32 v177, v177
	v_add_f32_e32 v176, 1.0, v176
	v_pk_mul_f32 v[36:37], v[36:37], v[174:175]
	v_add_f32_e32 v177, 1.0, v177
	v_rcp_f32_e32 v176, v176
	v_pk_mul_f32 v[36:37], v[32:33], v[36:37]
	v_rcp_f32_e32 v177, v177
	v_cvt_pk_bf16_f32 v32, v40, v41
	v_cvt_pk_bf16_f32 v33, v42, v43
	v_pk_mul_f32 v[176:177], v[38:39], v[176:177]
	s_nop 0
	v_pk_mul_f32 v[38:39], v[34:35], v[176:177]
	v_cvt_pk_bf16_f32 v34, v36, v37
	v_cvt_pk_bf16_f32 v35, v38, v39
	global_store_dwordx4 v[44:45], v[32:35], off
	s_nop 1
	v_mul_f32_e32 v170, 0xbfb8aa3b, v28
	v_mul_f32_e32 v171, 0xbfb8aa3b, v29
	v_add_u32_e32 v34, 0xa0, v144
	v_mul_f32_e32 v172, 0xbfb8aa3b, v30
	v_exp_f32_e32 v170, v170
	v_exp_f32_e32 v171, v171
	v_mul_f32_e32 v173, 0xbfb8aa3b, v31
	v_exp_f32_e32 v172, v172
	v_add_f32_e32 v170, 1.0, v170
	v_add_f32_e32 v171, 1.0, v171
	v_exp_f32_e32 v173, v173
	v_add_f32_e32 v172, 1.0, v172
	v_rcp_f32_e32 v170, v170
	v_rcp_f32_e32 v171, v171
	v_add_f32_e32 v173, 1.0, v173
	v_rcp_f32_e32 v172, v172
	v_mul_f32_e32 v174, 0xbfb8aa3b, v20
	v_pk_mul_f32 v[28:29], v[28:29], v[170:171]
	v_rcp_f32_e32 v173, v173
	v_mul_f32_e32 v175, 0xbfb8aa3b, v21
	v_exp_f32_e32 v174, v174
	v_pk_mul_f32 v[24:25], v[24:25], v[28:29]
	v_pk_mul_f32 v[172:173], v[30:31], v[172:173]
	v_exp_f32_e32 v175, v175
	v_add_f32_e32 v174, 1.0, v174
	v_mul_f32_e32 v176, 0xbfb8aa3b, v22
	v_pk_mul_f32 v[26:27], v[26:27], v[172:173]
	v_add_f32_e32 v175, 1.0, v175
	v_rcp_f32_e32 v174, v174
	v_mul_f32_e32 v177, 0xbfb8aa3b, v23
	v_exp_f32_e32 v176, v176
	v_rcp_f32_e32 v175, v175
	v_mad_i64_i32 v[28:29], s[30:31], v34, s1, v[138:139]
	v_exp_f32_e32 v177, v177
	v_add_f32_e32 v176, 1.0, v176
	v_pk_mul_f32 v[20:21], v[20:21], v[174:175]
	v_add_f32_e32 v177, 1.0, v177
	v_rcp_f32_e32 v176, v176
	v_pk_mul_f32 v[20:21], v[16:17], v[20:21]
	v_rcp_f32_e32 v177, v177
	v_cvt_pk_bf16_f32 v16, v24, v25
	v_cvt_pk_bf16_f32 v17, v26, v27
	v_pk_mul_f32 v[176:177], v[22:23], v[176:177]
	s_nop 0
	v_pk_mul_f32 v[22:23], v[18:19], v[176:177]
	v_cvt_pk_bf16_f32 v18, v20, v21
	v_cvt_pk_bf16_f32 v19, v22, v23
	global_store_dwordx4 v[28:29], v[16:19], off
	s_nop 1
	v_mul_f32_e32 v170, 0xbfb8aa3b, v12
	v_mul_f32_e32 v171, 0xbfb8aa3b, v13
	v_add_u32_e32 v18, 0xb0, v144
	v_mul_f32_e32 v172, 0xbfb8aa3b, v14
	v_exp_f32_e32 v170, v170
	v_exp_f32_e32 v171, v171
	v_mul_f32_e32 v173, 0xbfb8aa3b, v15
	v_exp_f32_e32 v172, v172
	v_add_f32_e32 v170, 1.0, v170
	v_add_f32_e32 v171, 1.0, v171
	v_exp_f32_e32 v173, v173
	v_add_f32_e32 v172, 1.0, v172
	v_rcp_f32_e32 v170, v170
	v_rcp_f32_e32 v171, v171
	v_add_f32_e32 v173, 1.0, v173
	v_rcp_f32_e32 v172, v172
	v_mul_f32_e32 v174, 0xbfb8aa3b, v4
	v_pk_mul_f32 v[12:13], v[12:13], v[170:171]
	v_rcp_f32_e32 v173, v173
	v_mul_f32_e32 v175, 0xbfb8aa3b, v5
	v_exp_f32_e32 v174, v174
	v_pk_mul_f32 v[8:9], v[8:9], v[12:13]
	v_pk_mul_f32 v[172:173], v[14:15], v[172:173]
	v_exp_f32_e32 v175, v175
	v_add_f32_e32 v174, 1.0, v174
	v_mul_f32_e32 v176, 0xbfb8aa3b, v6
	v_pk_mul_f32 v[10:11], v[10:11], v[172:173]
	v_add_f32_e32 v175, 1.0, v175
	v_rcp_f32_e32 v174, v174
	v_mul_f32_e32 v177, 0xbfb8aa3b, v7
	v_exp_f32_e32 v176, v176
	v_rcp_f32_e32 v175, v175
	v_mad_i64_i32 v[12:13], s[30:31], v18, s1, v[138:139]
	v_exp_f32_e32 v177, v177
	v_add_f32_e32 v176, 1.0, v176
	v_pk_mul_f32 v[4:5], v[4:5], v[174:175]
	v_add_f32_e32 v177, 1.0, v177
	v_rcp_f32_e32 v176, v176
	v_pk_mul_f32 v[4:5], v[0:1], v[4:5]
	v_rcp_f32_e32 v177, v177
	v_cvt_pk_bf16_f32 v0, v8, v9
	v_cvt_pk_bf16_f32 v1, v10, v11
	v_pk_mul_f32 v[176:177], v[6:7], v[176:177]
	s_nop 0
	v_pk_mul_f32 v[6:7], v[2:3], v[176:177]
	v_cvt_pk_bf16_f32 v2, v4, v5
	v_cvt_pk_bf16_f32 v3, v6, v7
	global_store_dwordx4 v[12:13], v[0:3], off
	s_andn2_b64 vcc, exec, s[40:41]
	s_mov_b64 s[30:31], -1
	s_cbranch_vccnz .LBB0_467
	s_andn2_b64 vcc, exec, s[2:3]
	s_cbranch_vccnz .LBB0_466
	s_barrier
	s_branch .LBB0_466
